# gemm256 K-loops: s_setprio 1 over each 8-MFMA group, s_setprio 0 before the next fragment ds_reads
# baseline (speedup 1.0000x reference)
; template <class Toff, class Setup, class Epi>
; DI void gemm256_stream(int tiles_per_xcd, int K, long ais, long akcs, long bis, Toff toff, Setup setup, Epi epi, char* smem) {
;     ...
;   const int nk = K >> 6;
;   __syncthreads();
;   G256_GLOAD(Ac, Bc, 0)
;   G256_SSTORE(0)
;   G256_GLOAD(Ac, Bc, 1)
;   __syncthreads();
;   while (true) {
;     const int qn = q + nj;
;     const bool has_next = qn < tiles_per_xcd;
;     if (has_next) setup(xcd, qn, An, Bn);
;     for (int kt = 0; kt < nk; ++kt) {
;       const int s = kt & 1;
;       const bool have1 = (kt + 1 < nk) || has_next;
;       const bool in_cur = (kt + 2 < nk);
;       const bool have2 = in_cur || (has_next && kt + 2 == nk);
;       const u16* Ap2 = in_cur ? Ac : An;
;       const u16* Bp2 = in_cur ? Bc : Bn;
;       const int kt2 = in_cur ? kt + 2 : kt + 2 - nk;
;       const char* base = smem + s * STAGE;
;       G256_KSTEP(0, ra0, rb0)
;       G256_KSTEP(1, ra1, rb1)
;       G256_KSTEP(2, ra2, rb2)
;       G256_KSTEP(3, ra3, rb3)
;       __syncthreads();
;     }
; DI void phase_x1(const Params& p, int l, char* smem) {
;     ...
;     auto setup = [&](int xcd, int q, const u16*& Ap, const u16*& Bp) __attribute__((always_inline)) {
;     G256_SETUP_IDS
;       const int mt = xcd * MPX + q % MPX, nt = q / MPX;
;       Ap = xb + (size_t)mt * 256 * D;
;       Bp = w + W_XQ + (size_t)nt * 256 * D;
;     };
;     auto toff = [&](int r0, int c8, int& aoff, int& boff) __attribute__((always_inline)) {
;       aoff = r0 * D + c8 * 8;
;       boff = r0 * D + c8 * 8;
;     };
.LBB0_109:
	s_and_b32 s6, s4, 0x10000
	s_add_i32 s5, s6, 0
	v_add_u32_e32 v0, s5, v216
	v_add3_u32 v174, v0, v220, v221
	v_add3_u32 v0, v0, v222, v221
	s_xor_b32 s6, s6, 0x10000
	s_setprio 0
	ds_read_b128 v[162:165], v174
	ds_read_b128 v[166:169], v174 offset:4096
	ds_read_b128 v[178:181], v174 offset:8192
	ds_read_b128 v[182:185], v174 offset:12288
	ds_read_b128 v[192:195], v0 offset:32768
	ds_read_b128 v[248:251], v0 offset:36864
	v_add_u32_e32 v0, s6, v215
	v_lshl_add_u64 v[174:175], v[172:173], 0, s[0:1]
	s_waitcnt vmcnt(7)
	ds_write_b128 v0, v[142:145]
	s_waitcnt vmcnt(6)
	ds_write_b128 v0, v[158:161] offset:32768
	v_add_co_u32_e32 v142, vcc, s7, v174
	v_lshl_add_u64 v[176:177], v[170:171], 0, s[0:1]
	s_nop 0
	v_addc_co_u32_e32 v143, vcc, 0, v175, vcc
	s_mov_b32 s6, 0x3820000
	v_add_co_u32_e32 v158, vcc, s6, v176
	global_load_dwordx4 v[142:145], v[142:143], off offset:3328
	s_nop 0
	v_addc_co_u32_e32 v159, vcc, 0, v177, vcc
	global_load_dwordx4 v[158:161], v[158:159], off offset:256
	s_waitcnt lgkmcnt(3)
	s_setprio 1
	v_mfma_f32_32x32x16_bf16 v[114:129], v[162:165], v[192:195], v[114:129]
	s_mov_b32 s6, 0x3840000
	v_mfma_f32_32x32x16_bf16 v[82:97], v[166:169], v[192:195], v[82:97]
	v_mfma_f32_32x32x16_bf16 v[50:65], v[178:181], v[192:195], v[50:65]
	v_mfma_f32_32x32x16_bf16 v[18:33], v[182:185], v[192:195], v[18:33]
	v_add_u32_e32 v192, s5, v217
	v_add3_u32 v247, v192, v222, v221
	s_waitcnt lgkmcnt(2)
	v_mfma_f32_32x32x16_bf16 v[2:17], v[182:185], v[248:251], v[2:17]
	v_add3_u32 v182, v192, v220, v221
	v_mfma_f32_32x32x16_bf16 v[98:113], v[162:165], v[248:251], v[98:113]
	v_mfma_f32_32x32x16_bf16 v[66:81], v[166:169], v[248:251], v[66:81]
	v_mfma_f32_32x32x16_bf16 v[34:49], v[178:181], v[248:251], v[34:49]
	s_setprio 0
	ds_read_b128 v[162:165], v182
	ds_read_b128 v[166:169], v182 offset:4096
	ds_read_b128 v[178:181], v182 offset:8192
	ds_read_b128 v[182:185], v182 offset:12288
	ds_read_b128 v[192:195], v247 offset:32768
	ds_read_b128 v[248:251], v247 offset:36864
	s_waitcnt vmcnt(7)
	ds_write_b128 v0, v[138:141] offset:8192
	s_waitcnt vmcnt(6)
	ds_write_b128 v0, v[154:157] offset:40960
	v_add_co_u32_e32 v138, vcc, s8, v174
	s_nop 1
	v_addc_co_u32_e32 v139, vcc, 0, v175, vcc
	v_add_co_u32_e32 v154, vcc, s6, v176
	global_load_dwordx4 v[138:141], v[138:139], off offset:3328
	s_nop 0
	v_addc_co_u32_e32 v155, vcc, 0, v177, vcc
	global_load_dwordx4 v[154:157], v[154:155], off offset:256
	s_waitcnt lgkmcnt(3)
	s_setprio 1
	v_mfma_f32_32x32x16_bf16 v[114:129], v[162:165], v[192:195], v[114:129]
	s_mov_b32 s6, 0x3860000
	v_mfma_f32_32x32x16_bf16 v[82:97], v[166:169], v[192:195], v[82:97]
	v_mfma_f32_32x32x16_bf16 v[50:65], v[178:181], v[192:195], v[50:65]
	v_mfma_f32_32x32x16_bf16 v[18:33], v[182:185], v[192:195], v[18:33]
	v_add_u32_e32 v192, s5, v218
	v_add3_u32 v247, v192, v222, v221
	s_waitcnt lgkmcnt(2)
	v_mfma_f32_32x32x16_bf16 v[2:17], v[182:185], v[248:251], v[2:17]
	v_add3_u32 v182, v192, v220, v221
	v_mfma_f32_32x32x16_bf16 v[98:113], v[162:165], v[248:251], v[98:113]
	v_mfma_f32_32x32x16_bf16 v[66:81], v[166:169], v[248:251], v[66:81]
	v_mfma_f32_32x32x16_bf16 v[34:49], v[178:181], v[248:251], v[34:49]
	s_setprio 0
	ds_read_b128 v[162:165], v182
	ds_read_b128 v[166:169], v182 offset:4096
	ds_read_b128 v[178:181], v182 offset:8192
	ds_read_b128 v[182:185], v182 offset:12288
	ds_read_b128 v[192:195], v247 offset:32768
	ds_read_b128 v[248:251], v247 offset:36864
	s_waitcnt vmcnt(7)
	ds_write_b128 v0, v[134:137] offset:16384
	s_waitcnt vmcnt(6)
	ds_write_b128 v0, v[150:153] offset:49152
	v_add_co_u32_e32 v134, vcc, s9, v174
	s_nop 1
	v_addc_co_u32_e32 v135, vcc, 0, v175, vcc
	v_add_co_u32_e32 v150, vcc, s6, v176
	global_load_dwordx4 v[134:137], v[134:135], off offset:3328
	s_nop 0
	v_addc_co_u32_e32 v151, vcc, 0, v177, vcc
	global_load_dwordx4 v[150:153], v[150:151], off offset:256
	s_waitcnt lgkmcnt(3)
	s_setprio 1
	v_mfma_f32_32x32x16_bf16 v[82:97], v[166:169], v[192:195], v[82:97]
	s_waitcnt lgkmcnt(2)
	v_mfma_f32_32x32x16_bf16 v[66:81], v[166:169], v[248:251], v[66:81]
	v_add_u32_e32 v166, s5, v219
	s_mov_b32 s5, 0x3880000
	v_mfma_f32_32x32x16_bf16 v[114:129], v[162:165], v[192:195], v[114:129]
	v_mfma_f32_32x32x16_bf16 v[98:113], v[162:165], v[248:251], v[98:113]
	v_add3_u32 v162, v166, v220, v221
	v_add3_u32 v166, v166, v222, v221
	v_mfma_f32_32x32x16_bf16 v[50:65], v[178:181], v[192:195], v[50:65]
	v_mfma_f32_32x32x16_bf16 v[34:49], v[178:181], v[248:251], v[34:49]
	v_mfma_f32_32x32x16_bf16 v[18:33], v[182:185], v[192:195], v[18:33]
	v_mfma_f32_32x32x16_bf16 v[2:17], v[182:185], v[248:251], v[2:17]
	s_setprio 0
	ds_read_b128 v[178:181], v162
	ds_read_b128 v[182:185], v162 offset:4096
	ds_read_b128 v[192:195], v162 offset:8192
	ds_read_b128 v[162:165], v162 offset:12288
	ds_read_b128 v[248:251], v166 offset:32768
	ds_read_b128 v[166:169], v166 offset:36864
	s_waitcnt vmcnt(7)
	ds_write_b128 v0, v[130:133] offset:24576
	s_waitcnt vmcnt(6)
	ds_write_b128 v0, v[146:149] offset:57344
	v_add_co_u32_e32 v130, vcc, s10, v174
	s_nop 1
	v_addc_co_u32_e32 v131, vcc, 0, v175, vcc
	v_add_co_u32_e32 v146, vcc, s5, v176
	global_load_dwordx4 v[130:133], v[130:131], off offset:3328
	s_nop 0
	v_addc_co_u32_e32 v147, vcc, 0, v177, vcc
	global_load_dwordx4 v[146:149], v[146:147], off offset:256
	s_waitcnt lgkmcnt(3)
	s_setprio 1
	v_mfma_f32_32x32x16_bf16 v[114:129], v[178:181], v[248:251], v[114:129]
	s_add_u32 s0, s0, 0x80
	s_addc_u32 s1, s1, 0
	s_add_i32 s4, s4, 0x10000
	s_cmpk_eq_i32 s0, 0x700
	s_waitcnt lgkmcnt(0)
	s_barrier
	v_mfma_f32_32x32x16_bf16 v[98:113], v[178:181], v[166:169], v[98:113]
	v_mfma_f32_32x32x16_bf16 v[82:97], v[182:185], v[248:251], v[82:97]
	v_mfma_f32_32x32x16_bf16 v[66:81], v[182:185], v[166:169], v[66:81]
	v_mfma_f32_32x32x16_bf16 v[50:65], v[192:195], v[248:251], v[50:65]
	v_mfma_f32_32x32x16_bf16 v[34:49], v[192:195], v[166:169], v[34:49]
	v_mfma_f32_32x32x16_bf16 v[18:33], v[162:165], v[248:251], v[18:33]
	v_mfma_f32_32x32x16_bf16 v[2:17], v[162:165], v[166:169], v[2:17]
	s_cbranch_scc0 .LBB0_109
	s_setprio 0
	s_add_i32 s7, s20, s58
	s_lshl_b32 s0, s7, 18
	s_and_b32 s0, s0, 0x3c0000
	s_lshl_b32 s1, s7, 14
	ds_read_b128 v[182:185], v231
	ds_read_b128 v[178:181], v231 offset:4096
	ds_read_b128 v[166:169], v231 offset:8192
	ds_read_b128 v[162:165], v231 offset:12288
	ds_read_b128 v[170:173], v232 offset:32768
	ds_read_b128 v[174:177], v232 offset:36864
	s_or_b32 s0, s0, s83
	s_and_b32 s4, s1, 0x40000
	s_cmp_lt_u32 s7, 32
	s_cselect_b64 s[10:11], -1, 0
	s_lshl_b32 s1, s0, 1
	s_add_u32 s8, s12, s1
	s_addc_u32 s9, s13, 0
	s_lshl_b32 s1, s4, 1
	s_add_u32 s22, s18, s1
	s_addc_u32 s23, s19, 0
	s_cmp_gt_u32 s7, 31
	v_lshl_add_u64 v[192:193], s[22:23], 0, v[186:187]
	v_lshl_add_u64 v[194:195], s[8:9], 0, v[186:187]
	s_waitcnt vmcnt(7)
	ds_write_b128 v223, v[142:145]
	s_waitcnt vmcnt(6)
	ds_write_b128 v224, v[158:161]
	s_cbranch_scc1 .LBB0_112
	global_load_dwordx4 v[142:145], v[194:195], off
	global_load_dwordx4 v[158:161], v[192:193], off

; template <class Toff, class Setup, class Epi>
; DI void gemm256_stream(int tiles_per_xcd, int K, long ais, long akcs, long bis, Toff toff, Setup setup, Epi epi, char* smem) {
;     ...
;   const int nk = K >> 6;
;   __syncthreads();
;   G256_GLOAD(Ac, Bc, 0)
;   G256_SSTORE(0)
;   G256_GLOAD(Ac, Bc, 1)
;   __syncthreads();
;   while (true) {
;     const int qn = q + nj;
;     const bool has_next = qn < tiles_per_xcd;
;     if (has_next) setup(xcd, qn, An, Bn);
;     for (int kt = 0; kt < nk; ++kt) {
;       const int s = kt & 1;
;       const bool have1 = (kt + 1 < nk) || has_next;
;       const bool in_cur = (kt + 2 < nk);
;       const bool have2 = in_cur || (has_next && kt + 2 == nk);
;       const u16* Ap2 = in_cur ? Ac : An;
;       const u16* Bp2 = in_cur ? Bc : Bn;
;       const int kt2 = in_cur ? kt + 2 : kt + 2 - nk;
;       const char* base = smem + s * STAGE;
;       G256_KSTEP(0, ra0, rb0)
;       G256_KSTEP(1, ra1, rb1)
;       G256_KSTEP(2, ra2, rb2)
;       G256_KSTEP(3, ra3, rb3)
;       __syncthreads();
;     }
; DI void phase_m4a(const Params& p, int l, int grp, char* smem) {
;     ...
;   auto setup = [&](int xcd, int q, const u16*& Ap, const u16*& Bp) __attribute__((always_inline)) {
;     G256_SETUP_IDS
;     const int mt = xcd * MPX + q % MPX, nt = q / MPX;
;     Ap = xb + (size_t)mt * 256 * D;
;     Bp = wt + (size_t)nt * 256 * D;
;   };
;   auto toff = [&](int r0, int c8, int& aoff, int& boff) __attribute__((always_inline)) {
;     aoff = r0 * D + c8 * 8;
;     boff = r0 * D + c8 * 8;
;   };
.LBB0_144:
	s_and_b32 s10, s7, 0x10000
	s_add_i32 s6, s10, 0
	v_add_u32_e32 v0, s6, v216
	v_add3_u32 v174, v0, v220, v221
	v_add3_u32 v0, v0, v222, v221
	s_xor_b32 s10, s10, 0x10000
	s_setprio 0
	ds_read_b128 v[162:165], v174
	ds_read_b128 v[166:169], v174 offset:4096
	ds_read_b128 v[178:181], v174 offset:8192
	ds_read_b128 v[182:185], v174 offset:12288
	ds_read_b128 v[192:195], v0 offset:32768
	ds_read_b128 v[248:251], v0 offset:36864
	v_add_u32_e32 v0, s10, v215
	v_lshl_add_u64 v[174:175], v[172:173], 0, s[8:9]
	s_waitcnt vmcnt(7)
	ds_write_b128 v0, v[142:145]
	s_waitcnt vmcnt(6)
	ds_write_b128 v0, v[158:161] offset:32768
	v_add_co_u32_e32 v142, vcc, s11, v174
	v_lshl_add_u64 v[176:177], v[170:171], 0, s[8:9]
	s_nop 0
	v_addc_co_u32_e32 v143, vcc, 0, v175, vcc
	s_mov_b32 s10, 0x2980000
	v_add_co_u32_e32 v158, vcc, s10, v176
	global_load_dwordx4 v[142:145], v[142:143], off offset:3328
	s_nop 0
	v_addc_co_u32_e32 v159, vcc, 0, v177, vcc
	global_load_dwordx4 v[158:161], v[158:159], off offset:256
	s_waitcnt lgkmcnt(3)
	s_setprio 1
	v_mfma_f32_32x32x16_bf16 v[114:129], v[162:165], v[192:195], v[114:129]
	s_mov_b32 s10, 0x29a0000
	v_mfma_f32_32x32x16_bf16 v[82:97], v[166:169], v[192:195], v[82:97]
	v_mfma_f32_32x32x16_bf16 v[50:65], v[178:181], v[192:195], v[50:65]
	v_mfma_f32_32x32x16_bf16 v[18:33], v[182:185], v[192:195], v[18:33]
	v_add_u32_e32 v192, s6, v217
	v_add3_u32 v247, v192, v222, v221
	s_waitcnt lgkmcnt(2)
	v_mfma_f32_32x32x16_bf16 v[2:17], v[182:185], v[248:251], v[2:17]
	v_add3_u32 v182, v192, v220, v221
	v_mfma_f32_32x32x16_bf16 v[98:113], v[162:165], v[248:251], v[98:113]
	v_mfma_f32_32x32x16_bf16 v[66:81], v[166:169], v[248:251], v[66:81]
	v_mfma_f32_32x32x16_bf16 v[34:49], v[178:181], v[248:251], v[34:49]
	s_setprio 0
	ds_read_b128 v[162:165], v182
	ds_read_b128 v[166:169], v182 offset:4096
	ds_read_b128 v[178:181], v182 offset:8192
	ds_read_b128 v[182:185], v182 offset:12288
	ds_read_b128 v[192:195], v247 offset:32768
	ds_read_b128 v[248:251], v247 offset:36864
	s_waitcnt vmcnt(7)
	ds_write_b128 v0, v[138:141] offset:8192
	s_waitcnt vmcnt(6)
	ds_write_b128 v0, v[154:157] offset:40960
	v_add_co_u32_e32 v138, vcc, s12, v174
	s_nop 1
	v_addc_co_u32_e32 v139, vcc, 0, v175, vcc
	v_add_co_u32_e32 v154, vcc, s10, v176
	global_load_dwordx4 v[138:141], v[138:139], off offset:3328
	s_nop 0
	v_addc_co_u32_e32 v155, vcc, 0, v177, vcc
	global_load_dwordx4 v[154:157], v[154:155], off offset:256
	s_waitcnt lgkmcnt(3)
	s_setprio 1
	v_mfma_f32_32x32x16_bf16 v[114:129], v[162:165], v[192:195], v[114:129]
	s_mov_b32 s10, 0x29c0000
	v_mfma_f32_32x32x16_bf16 v[82:97], v[166:169], v[192:195], v[82:97]
	v_mfma_f32_32x32x16_bf16 v[50:65], v[178:181], v[192:195], v[50:65]
	v_mfma_f32_32x32x16_bf16 v[18:33], v[182:185], v[192:195], v[18:33]
	v_add_u32_e32 v192, s6, v218
	v_add3_u32 v247, v192, v222, v221
	s_waitcnt lgkmcnt(2)
	v_mfma_f32_32x32x16_bf16 v[2:17], v[182:185], v[248:251], v[2:17]
	v_add3_u32 v182, v192, v220, v221
	v_mfma_f32_32x32x16_bf16 v[98:113], v[162:165], v[248:251], v[98:113]
	v_mfma_f32_32x32x16_bf16 v[66:81], v[166:169], v[248:251], v[66:81]
	v_mfma_f32_32x32x16_bf16 v[34:49], v[178:181], v[248:251], v[34:49]
	s_setprio 0
	ds_read_b128 v[162:165], v182
	ds_read_b128 v[166:169], v182 offset:4096
	ds_read_b128 v[178:181], v182 offset:8192
	ds_read_b128 v[182:185], v182 offset:12288
	ds_read_b128 v[192:195], v247 offset:32768
	ds_read_b128 v[248:251], v247 offset:36864
	s_waitcnt vmcnt(7)
	ds_write_b128 v0, v[134:137] offset:16384
	s_waitcnt vmcnt(6)
	ds_write_b128 v0, v[150:153] offset:49152
	v_add_co_u32_e32 v134, vcc, s13, v174
	s_nop 1
	v_addc_co_u32_e32 v135, vcc, 0, v175, vcc
	v_add_co_u32_e32 v150, vcc, s10, v176
	global_load_dwordx4 v[134:137], v[134:135], off offset:3328
	s_nop 0
	v_addc_co_u32_e32 v151, vcc, 0, v177, vcc
	global_load_dwordx4 v[150:153], v[150:151], off offset:256
	s_waitcnt lgkmcnt(3)
	s_setprio 1
	v_mfma_f32_32x32x16_bf16 v[82:97], v[166:169], v[192:195], v[82:97]
	s_waitcnt lgkmcnt(2)
	v_mfma_f32_32x32x16_bf16 v[66:81], v[166:169], v[248:251], v[66:81]
	v_add_u32_e32 v166, s6, v219
	s_mov_b32 s6, 0x29e0000
	v_mfma_f32_32x32x16_bf16 v[114:129], v[162:165], v[192:195], v[114:129]
	v_mfma_f32_32x32x16_bf16 v[98:113], v[162:165], v[248:251], v[98:113]
	v_add3_u32 v162, v166, v220, v221
	v_add3_u32 v166, v166, v222, v221
	v_mfma_f32_32x32x16_bf16 v[50:65], v[178:181], v[192:195], v[50:65]
	v_mfma_f32_32x32x16_bf16 v[34:49], v[178:181], v[248:251], v[34:49]
	v_mfma_f32_32x32x16_bf16 v[18:33], v[182:185], v[192:195], v[18:33]
	v_mfma_f32_32x32x16_bf16 v[2:17], v[182:185], v[248:251], v[2:17]
	s_setprio 0
	ds_read_b128 v[178:181], v162
	ds_read_b128 v[182:185], v162 offset:4096
	ds_read_b128 v[192:195], v162 offset:8192
	ds_read_b128 v[162:165], v162 offset:12288
	ds_read_b128 v[248:251], v166 offset:32768
	ds_read_b128 v[166:169], v166 offset:36864
	s_waitcnt vmcnt(7)
	ds_write_b128 v0, v[130:133] offset:24576
	s_waitcnt vmcnt(6)
	ds_write_b128 v0, v[146:149] offset:57344
	v_add_co_u32_e32 v130, vcc, s16, v174
	s_nop 1
	v_addc_co_u32_e32 v131, vcc, 0, v175, vcc
	v_add_co_u32_e32 v146, vcc, s6, v176
	global_load_dwordx4 v[130:133], v[130:131], off offset:3328
	s_nop 0
	v_addc_co_u32_e32 v147, vcc, 0, v177, vcc
	global_load_dwordx4 v[146:149], v[146:147], off offset:256
	s_waitcnt lgkmcnt(3)
	s_setprio 1
	v_mfma_f32_32x32x16_bf16 v[114:129], v[178:181], v[248:251], v[114:129]
	s_add_u32 s8, s8, 0x80
	s_addc_u32 s9, s9, 0
	s_add_i32 s7, s7, 0x10000
	s_cmpk_eq_i32 s8, 0x700
	s_waitcnt lgkmcnt(0)
	s_barrier
	v_mfma_f32_32x32x16_bf16 v[98:113], v[178:181], v[166:169], v[98:113]
	v_mfma_f32_32x32x16_bf16 v[82:97], v[182:185], v[248:251], v[82:97]
	v_mfma_f32_32x32x16_bf16 v[66:81], v[182:185], v[166:169], v[66:81]
	v_mfma_f32_32x32x16_bf16 v[50:65], v[192:195], v[248:251], v[50:65]
	v_mfma_f32_32x32x16_bf16 v[34:49], v[192:195], v[166:169], v[34:49]
	v_mfma_f32_32x32x16_bf16 v[18:33], v[162:165], v[248:251], v[18:33]
	v_mfma_f32_32x32x16_bf16 v[2:17], v[162:165], v[166:169], v[2:17]
	s_cbranch_scc0 .LBB0_144
	s_setprio 0
	s_add_i32 s22, s23, s58
	s_lshl_b32 s6, s22, 15
	s_and_b32 s10, s6, 0x3c0000
	s_lshl_b32 s6, s22, 18
	s_and_b32 s6, s6, 0x1c0000
	s_or_b32 s12, s6, s65
	ds_read_b128 v[182:185], v231
	ds_read_b128 v[178:181], v231 offset:4096
	ds_read_b128 v[166:169], v231 offset:8192
	ds_read_b128 v[162:165], v231 offset:12288
	ds_read_b128 v[170:173], v232 offset:32768
	ds_read_b128 v[174:177], v232 offset:36864
	s_lshl_b32 s6, s12, 1
	s_add_u32 s6, s18, s6
	s_addc_u32 s7, s19, 0
	s_cmpk_lt_u32 s22, 0x80
	s_cselect_b64 s[16:17], -1, 0
	s_lshl_b32 s8, s10, 1
	s_add_u32 s8, s20, s8
	s_addc_u32 s9, s21, 0
	s_cmpk_gt_u32 s22, 0x7f
	v_lshl_add_u64 v[192:193], s[8:9], 0, v[186:187]
	v_lshl_add_u64 v[194:195], s[6:7], 0, v[186:187]
	s_waitcnt vmcnt(7)
	ds_write_b128 v223, v[142:145]
	s_waitcnt vmcnt(6)
	ds_write_b128 v224, v[158:161]
	s_cbranch_scc1 .LBB0_147
	global_load_dwordx4 v[142:145], v[194:195], off
	global_load_dwordx4 v[158:161], v[192:193], off

; template <class Toff, class Setup, class Epi>
; DI void gemm256_stream(int tiles_per_xcd, int K, long ais, long akcs, long bis, Toff toff, Setup setup, Epi epi, char* smem) {
;     ...
;   const int nk = K >> 6;
;   __syncthreads();
;   G256_GLOAD(Ac, Bc, 0)
;   G256_SSTORE(0)
;   G256_GLOAD(Ac, Bc, 1)
;   __syncthreads();
;   while (true) {
;     const int qn = q + nj;
;     const bool has_next = qn < tiles_per_xcd;
;     if (has_next) setup(xcd, qn, An, Bn);
;     for (int kt = 0; kt < nk; ++kt) {
;       const int s = kt & 1;
;       const bool have1 = (kt + 1 < nk) || has_next;
;       const bool in_cur = (kt + 2 < nk);
;       const bool have2 = in_cur || (has_next && kt + 2 == nk);
;       const u16* Ap2 = in_cur ? Ac : An;
;       const u16* Bp2 = in_cur ? Bc : Bn;
;       const int kt2 = in_cur ? kt + 2 : kt + 2 - nk;
;       const char* base = smem + s * STAGE;
;       G256_KSTEP(0, ra0, rb0)
;       G256_KSTEP(1, ra1, rb1)
;       G256_KSTEP(2, ra2, rb2)
;       G256_KSTEP(3, ra3, rb3)
;       __syncthreads();
;     }
; DI void phase_m1(const Params& p, int l, int grp, char* smem) {
;     ...
;   auto setup = [&](int xcd, int q, const u16*& Ap, const u16*& Bp) __attribute__((always_inline)) {
;     G256_SETUP_IDS
;     const int mt = xcd * MPX + q % MPX, nt = q / MPX;
;     Ap = xb + (size_t)mt * 256 * D;
;     Bp = wt + (size_t)nt * 256 * D;
;   };
;   auto toff = [&](int r0, int c8, int& aoff, int& boff) __attribute__((always_inline)) {
;     aoff = r0 * D + c8 * 8;
;     boff = r0 * D + c8 * 8;
;   };
.LBB0_613:
	s_and_b32 s8, s7, 0x10000
	s_add_i32 s6, s8, 0
	v_add_u32_e32 v0, s6, v216
	v_add3_u32 v174, v0, v220, v221
	v_add3_u32 v0, v0, v222, v221
	s_xor_b32 s8, s8, 0x10000
	s_setprio 0
	ds_read_b128 v[162:165], v174
	ds_read_b128 v[166:169], v174 offset:4096
	ds_read_b128 v[178:181], v174 offset:8192
	ds_read_b128 v[182:185], v174 offset:12288
	ds_read_b128 v[192:195], v0 offset:32768
	ds_read_b128 v[248:251], v0 offset:36864
	v_add_u32_e32 v0, s8, v215
	v_lshl_add_u64 v[174:175], v[172:173], 0, s[0:1]
	s_waitcnt vmcnt(7)
	ds_write_b128 v0, v[142:145]
	s_waitcnt vmcnt(6)
	ds_write_b128 v0, v[158:161] offset:32768
	v_add_co_u32_e32 v142, vcc, s9, v174
	v_lshl_add_u64 v[176:177], v[170:171], 0, s[0:1]
	s_nop 0
	v_addc_co_u32_e32 v143, vcc, 0, v175, vcc
	s_mov_b32 s8, 0x2100000
	v_add_co_u32_e32 v158, vcc, s8, v176
	global_load_dwordx4 v[142:145], v[142:143], off offset:3328
	s_nop 0
	v_addc_co_u32_e32 v159, vcc, 0, v177, vcc
	global_load_dwordx4 v[158:161], v[158:159], off offset:256
	s_waitcnt lgkmcnt(3)
	s_setprio 1
	v_mfma_f32_32x32x16_bf16 v[114:129], v[162:165], v[192:195], v[114:129]
	s_mov_b32 s8, 0x2120000
	v_mfma_f32_32x32x16_bf16 v[82:97], v[166:169], v[192:195], v[82:97]
	v_mfma_f32_32x32x16_bf16 v[50:65], v[178:181], v[192:195], v[50:65]
	v_mfma_f32_32x32x16_bf16 v[18:33], v[182:185], v[192:195], v[18:33]
	v_add_u32_e32 v192, s6, v217
	v_add3_u32 v247, v192, v222, v221
	s_waitcnt lgkmcnt(2)
	v_mfma_f32_32x32x16_bf16 v[2:17], v[182:185], v[248:251], v[2:17]
	v_add3_u32 v182, v192, v220, v221
	v_mfma_f32_32x32x16_bf16 v[98:113], v[162:165], v[248:251], v[98:113]
	v_mfma_f32_32x32x16_bf16 v[66:81], v[166:169], v[248:251], v[66:81]
	v_mfma_f32_32x32x16_bf16 v[34:49], v[178:181], v[248:251], v[34:49]
	s_setprio 0
	ds_read_b128 v[162:165], v182
	ds_read_b128 v[166:169], v182 offset:4096
	ds_read_b128 v[178:181], v182 offset:8192
	ds_read_b128 v[182:185], v182 offset:12288
	ds_read_b128 v[192:195], v247 offset:32768
	ds_read_b128 v[248:251], v247 offset:36864
	s_waitcnt vmcnt(7)
	ds_write_b128 v0, v[138:141] offset:8192
	s_waitcnt vmcnt(6)
	ds_write_b128 v0, v[154:157] offset:40960
	v_add_co_u32_e32 v138, vcc, s10, v174
	s_nop 1
	v_addc_co_u32_e32 v139, vcc, 0, v175, vcc
	v_add_co_u32_e32 v154, vcc, s8, v176
	global_load_dwordx4 v[138:141], v[138:139], off offset:3328
	s_nop 0
	v_addc_co_u32_e32 v155, vcc, 0, v177, vcc
	global_load_dwordx4 v[154:157], v[154:155], off offset:256
	s_waitcnt lgkmcnt(3)
	s_setprio 1
	v_mfma_f32_32x32x16_bf16 v[114:129], v[162:165], v[192:195], v[114:129]
	s_mov_b32 s8, 0x2140000
	v_mfma_f32_32x32x16_bf16 v[82:97], v[166:169], v[192:195], v[82:97]
	v_mfma_f32_32x32x16_bf16 v[50:65], v[178:181], v[192:195], v[50:65]
	v_mfma_f32_32x32x16_bf16 v[18:33], v[182:185], v[192:195], v[18:33]
	v_add_u32_e32 v192, s6, v218
	v_add3_u32 v247, v192, v222, v221
	s_waitcnt lgkmcnt(2)
	v_mfma_f32_32x32x16_bf16 v[2:17], v[182:185], v[248:251], v[2:17]
	v_add3_u32 v182, v192, v220, v221
	v_mfma_f32_32x32x16_bf16 v[98:113], v[162:165], v[248:251], v[98:113]
	v_mfma_f32_32x32x16_bf16 v[66:81], v[166:169], v[248:251], v[66:81]
	v_mfma_f32_32x32x16_bf16 v[34:49], v[178:181], v[248:251], v[34:49]
	s_setprio 0
	ds_read_b128 v[162:165], v182
	ds_read_b128 v[166:169], v182 offset:4096
	ds_read_b128 v[178:181], v182 offset:8192
	ds_read_b128 v[182:185], v182 offset:12288
	ds_read_b128 v[192:195], v247 offset:32768
	ds_read_b128 v[248:251], v247 offset:36864
	s_waitcnt vmcnt(7)
	ds_write_b128 v0, v[134:137] offset:16384
	s_waitcnt vmcnt(6)
	ds_write_b128 v0, v[150:153] offset:49152
	v_add_co_u32_e32 v134, vcc, s11, v174
	s_nop 1
	v_addc_co_u32_e32 v135, vcc, 0, v175, vcc
	v_add_co_u32_e32 v150, vcc, s8, v176
	global_load_dwordx4 v[134:137], v[134:135], off offset:3328
	s_nop 0
	v_addc_co_u32_e32 v151, vcc, 0, v177, vcc
	global_load_dwordx4 v[150:153], v[150:151], off offset:256
	s_waitcnt lgkmcnt(3)
	s_setprio 1
	v_mfma_f32_32x32x16_bf16 v[82:97], v[166:169], v[192:195], v[82:97]
	s_waitcnt lgkmcnt(2)
	v_mfma_f32_32x32x16_bf16 v[66:81], v[166:169], v[248:251], v[66:81]
	v_add_u32_e32 v166, s6, v219
	s_mov_b32 s6, 0x2160000
	v_mfma_f32_32x32x16_bf16 v[114:129], v[162:165], v[192:195], v[114:129]
	v_mfma_f32_32x32x16_bf16 v[98:113], v[162:165], v[248:251], v[98:113]
	v_add3_u32 v162, v166, v220, v221
	v_add3_u32 v166, v166, v222, v221
	v_mfma_f32_32x32x16_bf16 v[50:65], v[178:181], v[192:195], v[50:65]
	v_mfma_f32_32x32x16_bf16 v[34:49], v[178:181], v[248:251], v[34:49]
	v_mfma_f32_32x32x16_bf16 v[18:33], v[182:185], v[192:195], v[18:33]
	v_mfma_f32_32x32x16_bf16 v[2:17], v[182:185], v[248:251], v[2:17]
	s_setprio 0
	ds_read_b128 v[178:181], v162
	ds_read_b128 v[182:185], v162 offset:4096
	ds_read_b128 v[192:195], v162 offset:8192
	ds_read_b128 v[162:165], v162 offset:12288
	ds_read_b128 v[248:251], v166 offset:32768
	ds_read_b128 v[166:169], v166 offset:36864
	s_waitcnt vmcnt(7)
	ds_write_b128 v0, v[130:133] offset:24576
	s_waitcnt vmcnt(6)
	ds_write_b128 v0, v[146:149] offset:57344
	v_add_co_u32_e32 v130, vcc, s17, v174
	s_nop 1
	v_addc_co_u32_e32 v131, vcc, 0, v175, vcc
	v_add_co_u32_e32 v146, vcc, s6, v176
	global_load_dwordx4 v[130:133], v[130:131], off offset:3328
	s_nop 0
	v_addc_co_u32_e32 v147, vcc, 0, v177, vcc
	global_load_dwordx4 v[146:149], v[146:147], off offset:256
	s_waitcnt lgkmcnt(3)
	s_setprio 1
	v_mfma_f32_32x32x16_bf16 v[114:129], v[178:181], v[248:251], v[114:129]
	s_add_u32 s0, s0, 0x80
	s_addc_u32 s1, s1, 0
	s_add_i32 s7, s7, 0x10000
	s_cmpk_eq_i32 s0, 0x700
	s_waitcnt lgkmcnt(0)
	s_barrier
	v_mfma_f32_32x32x16_bf16 v[98:113], v[178:181], v[166:169], v[98:113]
	v_mfma_f32_32x32x16_bf16 v[82:97], v[182:185], v[248:251], v[82:97]
	v_mfma_f32_32x32x16_bf16 v[66:81], v[182:185], v[166:169], v[66:81]
	v_mfma_f32_32x32x16_bf16 v[50:65], v[192:195], v[248:251], v[50:65]
	v_mfma_f32_32x32x16_bf16 v[34:49], v[192:195], v[166:169], v[34:49]
	v_mfma_f32_32x32x16_bf16 v[18:33], v[162:165], v[248:251], v[18:33]
	v_mfma_f32_32x32x16_bf16 v[2:17], v[162:165], v[166:169], v[2:17]
	s_cbranch_scc0 .LBB0_613
	s_setprio 0
	s_add_i32 s29, s16, s58
	s_lshl_b32 s0, s29, 15
	s_and_b32 s92, s0, 0x7c0000
	s_lshl_b32 s0, s29, 18
	s_and_b32 s0, s0, 0x1c0000
	s_or_b32 s76, s0, s65
	ds_read_b128 v[182:185], v231
	ds_read_b128 v[178:181], v231 offset:4096
	ds_read_b128 v[166:169], v231 offset:8192
	ds_read_b128 v[162:165], v231 offset:12288
	ds_read_b128 v[170:173], v232 offset:32768
	ds_read_b128 v[174:177], v232 offset:36864
	s_lshl_b32 s0, s76, 1
	s_add_u32 s0, s18, s0
	s_addc_u32 s1, s19, 0
	s_cmpk_lt_u32 s29, 0x88
	s_cselect_b64 s[86:87], -1, 0
	s_lshl_b32 s6, s92, 1
	s_add_u32 s6, s20, s6
	s_addc_u32 s7, s21, 0
	s_cmpk_gt_u32 s29, 0x87
	v_lshl_add_u64 v[192:193], s[6:7], 0, v[186:187]
	v_lshl_add_u64 v[194:195], s[0:1], 0, v[186:187]
	s_waitcnt vmcnt(7)
	ds_write_b128 v223, v[142:145]
	s_waitcnt vmcnt(6)
	ds_write_b128 v224, v[158:161]
	s_cbranch_scc1 .LBB0_616
	global_load_dwordx4 v[142:145], v[194:195], off
	global_load_dwordx4 v[158:161], v[192:193], off

; template <class Toff, class Setup, class Epi>
; DI void gemm256_stream(int tiles_per_xcd, int K, long ais, long akcs, long bis, Toff toff, Setup setup, Epi epi, char* smem) {
;     ...
;   const int nk = K >> 6;
;   __syncthreads();
;   G256_GLOAD(Ac, Bc, 0)
;   G256_SSTORE(0)
;   G256_GLOAD(Ac, Bc, 1)
;   __syncthreads();
;   while (true) {
;     const int qn = q + nj;
;     const bool has_next = qn < tiles_per_xcd;
;     if (has_next) setup(xcd, qn, An, Bn);
;     for (int kt = 0; kt < nk; ++kt) {
;       const int s = kt & 1;
;       const bool have1 = (kt + 1 < nk) || has_next;
;       const bool in_cur = (kt + 2 < nk);
;       const bool have2 = in_cur || (has_next && kt + 2 == nk);
;       const u16* Ap2 = in_cur ? Ac : An;
;       const u16* Bp2 = in_cur ? Bc : Bn;
;       const int kt2 = in_cur ? kt + 2 : kt + 2 - nk;
;       const char* base = smem + s * STAGE;
;       G256_KSTEP(0, ra0, rb0)
;       G256_KSTEP(1, ra1, rb1)
;       G256_KSTEP(2, ra2, rb2)
;       G256_KSTEP(3, ra3, rb3)
;       __syncthreads();
;     }
; DI void phase_gemm_resid(const Params& p, const u16* A, int lda, int K, const u16* Bt, bool last_sub, float scl,
;                          int row0, int nrows, char* smem) {
;     ...
;   auto setup = [&](int xcd, int q, const u16*& Ap, const u16*& Bp) __attribute__((always_inline)) {
;     G256_SETUP_IDS
;     const int mt = xcd * mpx + (q >> 5) * 8 + (q & 7), nt = (q >> 3) & 3;
;     Ap = A + (size_t)mt * 256 * lda;
;     Bp = Bt + (size_t)nt * 256 * K;
;   };
;   auto toff = [&](int r0, int c8, int& aoff, int& boff) __attribute__((always_inline)) {
;     aoff = r0 * lda + c8 * 8;
;     boff = r0 * K + c8 * 8;
;   };
.LBB0_825:
	s_and_b32 s49, s7, 0x10000
	s_add_i32 s6, s49, 0
	v_add_u32_e32 v178, s6, v192
	s_xor_b32 s49, s49, 0x10000
	v_add3_u32 v174, v178, v215, v216
	v_add3_u32 v182, v178, v217, v216
	v_add_u32_e32 v188, s49, v0
	s_setprio 0
	ds_read_b128 v[162:165], v174
	ds_read_b128 v[166:169], v174 offset:4096
	ds_read_b128 v[170:173], v174 offset:8192
	ds_read_b128 v[174:177], v174 offset:12288
	ds_read_b128 v[178:181], v182 offset:32768
	ds_read_b128 v[182:185], v182 offset:36864
	s_waitcnt vmcnt(7)
	ds_write_b128 v188, v[146:149]
	s_waitcnt vmcnt(6)
	ds_write_b128 v188, v[158:161] offset:32768
	v_lshl_add_u64 v[146:147], s[8:9], 0, v[186:187]
	v_lshl_add_u64 v[158:159], s[22:23], 0, v[186:187]
	global_load_dwordx4 v[146:149], v[146:147], off
	s_add_i32 s35, s35, 1
	global_load_dwordx4 v[158:161], v[158:159], off
	s_waitcnt lgkmcnt(3)
	s_setprio 1
	v_mfma_f32_32x32x16_bf16 v[114:129], v[162:165], v[178:181], v[114:129]
	v_mfma_f32_32x32x16_bf16 v[82:97], v[166:169], v[178:181], v[82:97]
	v_mfma_f32_32x32x16_bf16 v[50:65], v[170:173], v[178:181], v[50:65]
	v_mfma_f32_32x32x16_bf16 v[18:33], v[174:177], v[178:181], v[18:33]
	v_add_u32_e32 v178, s6, v193
	s_waitcnt lgkmcnt(2)
	v_mfma_f32_32x32x16_bf16 v[98:113], v[162:165], v[182:185], v[98:113]
	v_mfma_f32_32x32x16_bf16 v[66:81], v[166:169], v[182:185], v[66:81]
	v_mfma_f32_32x32x16_bf16 v[34:49], v[170:173], v[182:185], v[34:49]
	v_mfma_f32_32x32x16_bf16 v[2:17], v[174:177], v[182:185], v[2:17]
	v_add3_u32 v174, v178, v215, v216
	v_add3_u32 v182, v178, v217, v216
	s_setprio 0
	ds_read_b128 v[162:165], v174
	ds_read_b128 v[166:169], v174 offset:4096
	ds_read_b128 v[170:173], v174 offset:8192
	ds_read_b128 v[174:177], v174 offset:12288
	ds_read_b128 v[178:181], v182 offset:32768
	ds_read_b128 v[182:185], v182 offset:36864
	s_waitcnt vmcnt(7)
	ds_write_b128 v188, v[138:141] offset:8192
	s_waitcnt vmcnt(6)
	ds_write_b128 v188, v[154:157] offset:40960
	v_lshl_add_u64 v[138:139], s[20:21], 0, v[186:187]
	v_lshl_add_u64 v[154:155], s[28:29], 0, v[186:187]
	global_load_dwordx4 v[138:141], v[138:139], off
	s_nop 0
	global_load_dwordx4 v[154:157], v[154:155], off
	s_waitcnt lgkmcnt(3)
	s_setprio 1
	v_mfma_f32_32x32x16_bf16 v[114:129], v[162:165], v[178:181], v[114:129]
	v_mfma_f32_32x32x16_bf16 v[82:97], v[166:169], v[178:181], v[82:97]
	v_mfma_f32_32x32x16_bf16 v[50:65], v[170:173], v[178:181], v[50:65]
	v_mfma_f32_32x32x16_bf16 v[18:33], v[174:177], v[178:181], v[18:33]
	v_add_u32_e32 v178, s6, v194
	s_waitcnt lgkmcnt(2)
	v_mfma_f32_32x32x16_bf16 v[98:113], v[162:165], v[182:185], v[98:113]
	v_mfma_f32_32x32x16_bf16 v[66:81], v[166:169], v[182:185], v[66:81]
	v_mfma_f32_32x32x16_bf16 v[34:49], v[170:173], v[182:185], v[34:49]
	v_mfma_f32_32x32x16_bf16 v[2:17], v[174:177], v[182:185], v[2:17]
	v_add3_u32 v174, v178, v215, v216
	v_add3_u32 v182, v178, v217, v216
	s_setprio 0
	ds_read_b128 v[162:165], v174
	ds_read_b128 v[166:169], v174 offset:4096
	ds_read_b128 v[170:173], v174 offset:8192
	ds_read_b128 v[174:177], v174 offset:12288
	ds_read_b128 v[178:181], v182 offset:32768
	ds_read_b128 v[182:185], v182 offset:36864
	s_waitcnt vmcnt(7)
	ds_write_b128 v188, v[134:137] offset:16384
	s_waitcnt vmcnt(6)
	ds_write_b128 v188, v[150:153] offset:49152
	v_lshl_add_u64 v[134:135], s[18:19], 0, v[186:187]
	v_lshl_add_u64 v[150:151], s[26:27], 0, v[186:187]
	global_load_dwordx4 v[134:137], v[134:135], off
	s_nop 0
	global_load_dwordx4 v[150:153], v[150:151], off
	s_waitcnt lgkmcnt(3)
	s_setprio 1
	v_mfma_f32_32x32x16_bf16 v[82:97], v[166:169], v[178:181], v[82:97]
	s_waitcnt lgkmcnt(2)
	v_mfma_f32_32x32x16_bf16 v[66:81], v[166:169], v[182:185], v[66:81]
	v_add_u32_e32 v166, s6, v195
	v_mfma_f32_32x32x16_bf16 v[114:129], v[162:165], v[178:181], v[114:129]
	v_mfma_f32_32x32x16_bf16 v[98:113], v[162:165], v[182:185], v[98:113]
	v_add3_u32 v162, v166, v215, v216
	v_add3_u32 v166, v166, v217, v216
	v_mfma_f32_32x32x16_bf16 v[50:65], v[170:173], v[178:181], v[50:65]
	v_mfma_f32_32x32x16_bf16 v[34:49], v[170:173], v[182:185], v[34:49]
	v_mfma_f32_32x32x16_bf16 v[18:33], v[174:177], v[178:181], v[18:33]
	v_mfma_f32_32x32x16_bf16 v[2:17], v[174:177], v[182:185], v[2:17]
	s_setprio 0
	ds_read_b128 v[178:181], v162
	ds_read_b128 v[182:185], v162 offset:4096
	ds_read_b128 v[174:177], v162 offset:8192
	ds_read_b128 v[162:165], v162 offset:12288
	ds_read_b128 v[170:173], v166 offset:32768
	ds_read_b128 v[166:169], v166 offset:36864
	s_waitcnt vmcnt(7)
	ds_write_b128 v188, v[130:133] offset:24576
	s_waitcnt vmcnt(6)
	ds_write_b128 v188, v[142:145] offset:57344
	v_lshl_add_u64 v[130:131], s[16:17], 0, v[186:187]
	v_lshl_add_u64 v[142:143], s[24:25], 0, v[186:187]
	global_load_dwordx4 v[130:133], v[130:131], off
	s_nop 0
	global_load_dwordx4 v[142:145], v[142:143], off
	s_add_i32 s7, s7, 0x10000
	s_add_u32 s16, s16, 0x80
	s_addc_u32 s17, s17, 0
	s_add_u32 s18, s18, 0x80
	s_addc_u32 s19, s19, 0
	s_add_u32 s20, s20, 0x80
	s_addc_u32 s21, s21, 0
	s_add_u32 s8, s8, 0x80
	s_addc_u32 s9, s9, 0
	s_add_u32 s24, s24, 0x80
	s_waitcnt lgkmcnt(3)
	s_setprio 1
	v_mfma_f32_32x32x16_bf16 v[114:129], v[178:181], v[170:173], v[114:129]
	s_addc_u32 s25, s25, 0
	s_add_u32 s26, s26, 0x80
	s_addc_u32 s27, s27, 0
	s_add_u32 s28, s28, 0x80
	s_addc_u32 s29, s29, 0
	s_add_u32 s22, s22, 0x80
	s_addc_u32 s23, s23, 0
	s_waitcnt lgkmcnt(2)
	v_mfma_f32_32x32x16_bf16 v[98:113], v[178:181], v[166:169], v[98:113]
	s_cmp_eq_u32 s44, s35
	s_waitcnt lgkmcnt(0)
	s_barrier
	v_mfma_f32_32x32x16_bf16 v[82:97], v[182:185], v[170:173], v[82:97]
	v_mfma_f32_32x32x16_bf16 v[66:81], v[182:185], v[166:169], v[66:81]
	v_mfma_f32_32x32x16_bf16 v[50:65], v[174:177], v[170:173], v[50:65]
	v_mfma_f32_32x32x16_bf16 v[34:49], v[174:177], v[166:169], v[34:49]
	v_mfma_f32_32x32x16_bf16 v[18:33], v[162:165], v[170:173], v[18:33]
	v_mfma_f32_32x32x16_bf16 v[2:17], v[162:165], v[166:169], v[2:17]
	s_cbranch_scc0 .LBB0_825
	s_setprio 0
	s_lshl_b32 s6, s44, 16
	s_and_b32 s7, s6, 0x10000
	s_add_i32 s6, s7, 0
	v_add_u32_e32 v170, s6, v192
	v_add3_u32 v162, v170, v215, v216
	ds_read_b128 v[182:185], v162
	ds_read_b128 v[178:181], v162 offset:4096
	ds_read_b128 v[166:169], v162 offset:8192
	ds_read_b128 v[162:165], v162 offset:12288
	v_add3_u32 v174, v170, v217, v216
	ds_read_b128 v[170:173], v174 offset:32768
	ds_read_b128 v[174:177], v174 offset:36864
	s_xor_b32 s7, s7, 0x10000
	v_cndmask_b32_e64 v188, 0, 1, s[0:1]
	v_add_u32_e32 v226, s7, v0
	v_cmp_ne_u32_e64 s[8:9], 1, v188
	s_andn2_b64 vcc, exec, s[0:1]
	v_lshl_add_u64 v[190:191], s[84:85], 0, v[186:187]
	v_lshl_add_u64 v[188:189], s[92:93], 0, v[186:187]
	s_waitcnt vmcnt(7)
	ds_write_b128 v226, v[146:149]
	s_waitcnt vmcnt(6)
	ds_write_b128 v226, v[158:161] offset:32768
	s_cbranch_vccnz .LBB0_828
	global_load_dwordx4 v[146:149], v[190:191], off
	global_load_dwordx4 v[158:161], v[188:189], off

; template <class Toff, class Setup, class Epi>
; DI void gemm256_stream(int tiles_per_xcd, int K, long ais, long akcs, long bis, Toff toff, Setup setup, Epi epi, char* smem) {
;     ...
;   const int nk = K >> 6;
;   __syncthreads();
;   G256_GLOAD(Ac, Bc, 0)
;   G256_SSTORE(0)
;   G256_GLOAD(Ac, Bc, 1)
;   __syncthreads();
;   while (true) {
;     const int qn = q + nj;
;     const bool has_next = qn < tiles_per_xcd;
;     if (has_next) setup(xcd, qn, An, Bn);
;     for (int kt = 0; kt < nk; ++kt) {
;       const int s = kt & 1;
;       const bool have1 = (kt + 1 < nk) || has_next;
;       const bool in_cur = (kt + 2 < nk);
;       const bool have2 = in_cur || (has_next && kt + 2 == nk);
;       const u16* Ap2 = in_cur ? Ac : An;
;       const u16* Bp2 = in_cur ? Bc : Bn;
;       const int kt2 = in_cur ? kt + 2 : kt + 2 - nk;
;       const char* base = smem + s * STAGE;
;       G256_KSTEP(0, ra0, rb0)
;       G256_KSTEP(1, ra1, rb1)
;       G256_KSTEP(2, ra2, rb2)
;       G256_KSTEP(3, ra3, rb3)
;       __syncthreads();
;     }
; DI void phase_ffn_up(const Params& p, const u16* w1t, const u16* w3t, char* smem) {
;     ...
;   auto setup = [&](int xcd, int q, const u16*& Ap, const u16*& Bp) __attribute__((always_inline)) {
;     G256_SETUP_IDS
;     const int mt = xcd * MPX + (q / (4 * (FF / 128))) * 4 + (q & 3), nt = (q >> 2) % (FF / 128);
;     Ap = xb + (size_t)mt * 256 * D;
;     Bp = w1t + (size_t)nt * 128 * D;
;   };
;   const int w3off = (int)(w3t - w1t);
;   auto toff = [&](int r0, int c8, int& aoff, int& boff) __attribute__((always_inline)) {
;     aoff = r0 * D + c8 * 8;
;     boff = ((r0 < 32) ? 0 : w3off) + (r0 & 31) * D + c8 * 8;
;   };
.LBB0_853:
	s_and_b32 s14, s7, 0x10000
	s_add_i32 s6, s14, 0
	v_add_u32_e32 v0, s6, v195
	v_add3_u32 v174, v0, v218, v219
	v_add3_u32 v0, v0, v220, v219
	s_xor_b32 s14, s14, 0x10000
	s_setprio 0
	ds_read_b128 v[162:165], v174
	ds_read_b128 v[166:169], v174 offset:4096
	ds_read_b128 v[178:181], v174 offset:8192
	ds_read_b128 v[182:185], v174 offset:12288
	ds_read_b128 v[190:193], v0 offset:32768
	ds_read_b128 v[246:249], v0 offset:36864
	v_add_u32_e32 v0, s14, v194
	s_waitcnt vmcnt(7)
	ds_write_b128 v0, v[142:145]
	s_waitcnt vmcnt(6)
	ds_write_b128 v0, v[158:161] offset:32768
	v_lshl_add_u64 v[176:177], v[170:171], 0, s[8:9]
	v_lshl_add_u64 v[174:175], v[172:173], 0, s[8:9]
	global_load_dwordx4 v[142:145], v[176:177], off offset:256
	global_load_dwordx4 v[158:161], v[174:175], off offset:256
	s_waitcnt lgkmcnt(3)
	s_setprio 1
	v_mfma_f32_32x32x16_bf16 v[114:129], v[162:165], v[190:193], v[114:129]
	v_mfma_f32_32x32x16_bf16 v[82:97], v[166:169], v[190:193], v[82:97]
	v_mfma_f32_32x32x16_bf16 v[50:65], v[178:181], v[190:193], v[50:65]
	v_mfma_f32_32x32x16_bf16 v[18:33], v[182:185], v[190:193], v[18:33]
	v_add_u32_e32 v190, s6, v215
	v_add3_u32 v245, v190, v220, v219
	s_waitcnt lgkmcnt(2)
	v_mfma_f32_32x32x16_bf16 v[2:17], v[182:185], v[246:249], v[2:17]
	v_add3_u32 v182, v190, v218, v219
	v_mfma_f32_32x32x16_bf16 v[98:113], v[162:165], v[246:249], v[98:113]
	v_mfma_f32_32x32x16_bf16 v[66:81], v[166:169], v[246:249], v[66:81]
	v_mfma_f32_32x32x16_bf16 v[34:49], v[178:181], v[246:249], v[34:49]
	s_setprio 0
	ds_read_b128 v[162:165], v182
	ds_read_b128 v[166:169], v182 offset:4096
	ds_read_b128 v[178:181], v182 offset:8192
	ds_read_b128 v[182:185], v182 offset:12288
	ds_read_b128 v[190:193], v245 offset:32768
	ds_read_b128 v[246:249], v245 offset:36864
	s_waitcnt vmcnt(7)
	ds_write_b128 v0, v[138:141] offset:8192
	s_waitcnt vmcnt(6)
	ds_write_b128 v0, v[154:157] offset:40960
	v_add_co_u32_e32 v138, vcc, s23, v176
	s_nop 1
	v_addc_co_u32_e32 v139, vcc, 0, v177, vcc
	v_add_co_u32_e32 v154, vcc, s25, v174
	global_load_dwordx4 v[138:141], v[138:139], off offset:256
	s_nop 0
	v_addc_co_u32_e32 v155, vcc, 0, v175, vcc
	global_load_dwordx4 v[154:157], v[154:155], off offset:256
	s_waitcnt lgkmcnt(3)
	s_setprio 1
	v_mfma_f32_32x32x16_bf16 v[114:129], v[162:165], v[190:193], v[114:129]
	v_mfma_f32_32x32x16_bf16 v[82:97], v[166:169], v[190:193], v[82:97]
	v_mfma_f32_32x32x16_bf16 v[50:65], v[178:181], v[190:193], v[50:65]
	v_mfma_f32_32x32x16_bf16 v[18:33], v[182:185], v[190:193], v[18:33]
	v_add_u32_e32 v190, s6, v216
	v_add3_u32 v245, v190, v220, v219
	s_waitcnt lgkmcnt(2)
	v_mfma_f32_32x32x16_bf16 v[2:17], v[182:185], v[246:249], v[2:17]
	v_add3_u32 v182, v190, v218, v219
	v_mfma_f32_32x32x16_bf16 v[98:113], v[162:165], v[246:249], v[98:113]
	v_mfma_f32_32x32x16_bf16 v[66:81], v[166:169], v[246:249], v[66:81]
	v_mfma_f32_32x32x16_bf16 v[34:49], v[178:181], v[246:249], v[34:49]
	s_setprio 0
	ds_read_b128 v[162:165], v182
	ds_read_b128 v[166:169], v182 offset:4096
	ds_read_b128 v[178:181], v182 offset:8192
	ds_read_b128 v[182:185], v182 offset:12288
	ds_read_b128 v[190:193], v245 offset:32768
	ds_read_b128 v[246:249], v245 offset:36864
	s_waitcnt vmcnt(7)
	ds_write_b128 v0, v[134:137] offset:16384
	s_waitcnt vmcnt(6)
	ds_write_b128 v0, v[150:153] offset:49152
	v_add_co_u32_e32 v134, vcc, s22, v176
	s_nop 1
	v_addc_co_u32_e32 v135, vcc, 0, v177, vcc
	v_add_co_u32_e32 v150, vcc, s23, v174
	global_load_dwordx4 v[134:137], v[134:135], off offset:256
	s_nop 0
	v_addc_co_u32_e32 v151, vcc, 0, v175, vcc
	global_load_dwordx4 v[150:153], v[150:151], off offset:256
	s_waitcnt lgkmcnt(3)
	s_setprio 1
	v_mfma_f32_32x32x16_bf16 v[82:97], v[166:169], v[190:193], v[82:97]
	s_waitcnt lgkmcnt(2)
	v_mfma_f32_32x32x16_bf16 v[66:81], v[166:169], v[246:249], v[66:81]
	v_add_u32_e32 v166, s6, v217
	v_mfma_f32_32x32x16_bf16 v[114:129], v[162:165], v[190:193], v[114:129]
	v_mfma_f32_32x32x16_bf16 v[98:113], v[162:165], v[246:249], v[98:113]
	v_add3_u32 v162, v166, v218, v219
	v_add3_u32 v166, v166, v220, v219
	v_mfma_f32_32x32x16_bf16 v[50:65], v[178:181], v[190:193], v[50:65]
	v_mfma_f32_32x32x16_bf16 v[34:49], v[178:181], v[246:249], v[34:49]
	v_mfma_f32_32x32x16_bf16 v[18:33], v[182:185], v[190:193], v[18:33]
	v_mfma_f32_32x32x16_bf16 v[2:17], v[182:185], v[246:249], v[2:17]
	s_setprio 0
	ds_read_b128 v[178:181], v162
	ds_read_b128 v[182:185], v162 offset:4096
	ds_read_b128 v[190:193], v162 offset:8192
	ds_read_b128 v[162:165], v162 offset:12288
	ds_read_b128 v[246:249], v166 offset:32768
	ds_read_b128 v[166:169], v166 offset:36864
	s_waitcnt vmcnt(7)
	ds_write_b128 v0, v[130:133] offset:24576
	s_waitcnt vmcnt(6)
	ds_write_b128 v0, v[146:149] offset:57344
	v_add_co_u32_e32 v130, vcc, s24, v176
	s_nop 1
	v_addc_co_u32_e32 v131, vcc, 0, v177, vcc
	v_add_co_u32_e32 v146, vcc, s26, v174
	global_load_dwordx4 v[130:133], v[130:131], off offset:256
	s_nop 0
	v_addc_co_u32_e32 v147, vcc, 0, v175, vcc
	global_load_dwordx4 v[146:149], v[146:147], off offset:256
	s_waitcnt lgkmcnt(3)
	s_setprio 1
	v_mfma_f32_32x32x16_bf16 v[114:129], v[178:181], v[246:249], v[114:129]
	s_add_u32 s8, s8, 0x80
	s_addc_u32 s9, s9, 0
	s_add_i32 s7, s7, 0x10000
	s_cmpk_eq_i32 s8, 0x700
	s_waitcnt lgkmcnt(0)
	s_barrier
	v_mfma_f32_32x32x16_bf16 v[98:113], v[178:181], v[166:169], v[98:113]
	v_mfma_f32_32x32x16_bf16 v[82:97], v[182:185], v[246:249], v[82:97]
	v_mfma_f32_32x32x16_bf16 v[66:81], v[182:185], v[166:169], v[66:81]
	v_mfma_f32_32x32x16_bf16 v[50:65], v[190:193], v[246:249], v[50:65]
	v_mfma_f32_32x32x16_bf16 v[34:49], v[190:193], v[166:169], v[34:49]
	v_mfma_f32_32x32x16_bf16 v[18:33], v[162:165], v[246:249], v[18:33]
	v_mfma_f32_32x32x16_bf16 v[2:17], v[162:165], v[166:169], v[2:17]
	s_cbranch_scc0 .LBB0_853
	s_setprio 0
	ds_read_b128 v[182:185], v229
	ds_read_b128 v[178:181], v229 offset:4096
	ds_read_b128 v[166:169], v229 offset:8192
	ds_read_b128 v[162:165], v229 offset:12288
	ds_read_b128 v[170:173], v230 offset:32768
	ds_read_b128 v[174:177], v230 offset:36864
	v_cndmask_b32_e64 v0, 0, 1, s[12:13]
	v_cmp_ne_u32_e64 s[8:9], 1, v0
	s_andn2_b64 vcc, exec, s[12:13]
	v_lshl_add_u64 v[190:191], v[188:189], 1, s[10:11]
	v_lshl_add_u64 v[192:193], v[186:187], 1, s[4:5]
	s_waitcnt vmcnt(7)
	ds_write_b128 v221, v[142:145]
	s_waitcnt vmcnt(6)
	ds_write_b128 v222, v[158:161]
	s_cbranch_vccnz .LBB0_856
	global_load_dwordx4 v[142:145], v[192:193], off
	global_load_dwordx4 v[158:161], v[190:191], off
